# P4 SSD pass C: Hprev fragment loads 9-deep in flight (was load-wait-mfma x16), norm-weight loads hoisted above the sub-block barrier
# baseline (speedup 1.0000x reference)
; #define LAS __attribute__((address_space(3)))
; __device__ __forceinline__ f32x16 zero16() { f32x16 z; for (int i = 0; i < 16; ++i) z[i] = 0.f; return z; }
; __device__ __forceinline__ void ssd_passC_unit(const Args& a, LAS unsigned char* lds, int unit, int tid, int w4, int lane, LAS unsigned* bcnt, unsigned& btarget) {
;     ...
;     const int h4 = w4, r = lane & 31, hf = lane >> 5, h = g * 4 + h4;
;     const LAS bf16_t* XT = (const LAS bf16_t*)(lds + L_XT) + h4 * 64 * XT_LD; const LAS bf16_t* Bn = (const LAS bf16_t*)(lds + L_BT); const LAS bf16_t* Cn = (const LAS bf16_t*)(lds + L_CN);
;     const LAS float* cs = (const LAS float*)(lds + L_CS) + h4 * 64; const LAS float* dtl = cs + 256; const LAS float* ecs = cs + 512; LAS float* red = (LAS float*)(lds + L_CS) + 768;
; #pragma unroll 1
;     for (int lh = 0; lh < 2; ++lh) {
;     const int l = lh * 32 + r;
;     const int row = si.row0 + l;
;     const bool realtok = l >= si.pad;
;     const bf16_t* zrow = (const bf16_t*)(a.ws + WS_PROJ) + (size_t)row * NPROJ + g * 256 + h4 * 64;
;     u32x2 zq[2][4];
; #pragma unroll
;     for (int pt = 0; pt < 2; ++pt)
; #pragma unroll
;         for (int i = 0; i < 4; ++i) zq[pt][i] = *(const u32x2*)(zrow + pt * 32 + 8 * i + 4 * hf);
;     bf16x8 cf[8];
; #pragma unroll
;     for (int ks = 0; ks < 8; ++ks) cf[ks] = *(const LAS bf16x8*)(Cn + l * BN_LD + ks * 16 + 8 * hf);
;     f32x16 ya[2]; ya[0] = zero16(); ya[1] = zero16();
;     const bf16_t* hp = (const bf16_t*)(a.ws + WS_SST) + ((size_t)si.slot * 8 + h) * 8192;
.LBB0_838:
	s_ashr_i32 s53, s52, 31
	s_or_b32 s17, s23, s18
	s_lshl_b64 s[0:1], s[52:53], 17
	s_lshl_b32 s20, s17, 14
	s_lshl_b32 s30, s16, 9
	s_add_u32 s0, s96, s0
	v_xor_b32_e32 v0, 32, v246
	v_add_u32_e32 v1, 64, v143
	s_addc_u32 s1, s97, s1
	v_cmp_lt_i32_e32 vcc, v0, v1
	s_add_u32 s0, s0, s20
	s_addc_u32 s1, s1, 0
	v_cndmask_b32_e32 v0, v246, v0, vcc
	v_mov_b32_e32 v143, v109
	v_lshlrev_b32_e32 v251, 2, v0
	v_lshl_add_u64 v[0:1], s[0:1], 0, v[142:143]
	v_mov_b32_e32 v147, v109
	v_lshl_add_u64 v[84:85], v[0:1], 0, v[146:147]
	s_lshl_b32 s0, s17, 2
	s_add_u32 s20, s78, s0
	s_addc_u32 s21, s79, 0
	s_lshl_b32 s0, s16, 10
	s_add_u32 s0, s80, s0
	s_addc_u32 s1, s81, 0
	v_mov_b32_e32 v145, v109
	s_add_u32 s52, s28, s30
	v_mov_b32_e32 v149, v109
	v_mov_b32_e32 v151, v109
	v_mov_b32_e32 v153, v109
	v_mov_b32_e32 v155, v109
	v_mov_b32_e32 v157, v109
	v_mov_b32_e32 v159, v109
	v_mov_b32_e32 v161, v109
	v_mov_b32_e32 v163, v109
	v_lshl_add_u64 v[80:81], v[140:141], 0, s[30:31]
	v_lshl_add_u64 v[82:83], v[0:1], 0, v[144:145]
	s_addc_u32 s53, s29, 0
	v_lshl_add_u64 v[100:101], s[0:1], 0, v[148:149]
	v_lshl_add_u64 v[102:103], s[0:1], 0, v[150:151]
	v_lshl_add_u64 v[104:105], s[0:1], 0, v[152:153]
	v_lshl_add_u64 v[164:165], s[0:1], 0, v[154:155]
	v_lshl_add_u64 v[166:167], s[0:1], 0, v[156:157]
	v_lshl_add_u64 v[168:169], s[0:1], 0, v[158:159]
	v_lshl_add_u64 v[170:171], s[0:1], 0, v[160:161]
	v_lshl_add_u64 v[172:173], s[0:1], 0, v[162:163]
	s_mov_b32 s16, 0
	s_mov_b64 s[0:1], -1
	s_branch .LBB0_840

; #define LAS __attribute__((address_space(3)))
; #define MFMA32(a, b, c) __builtin_amdgcn_mfma_f32_32x32x16_bf16((a), (b), (c), 0, 0, 0)
; __device__ __forceinline__ f32x16 zero16() { f32x16 z; for (int i = 0; i < 16; ++i) z[i] = 0.f; return z; }
; __device__ __forceinline__ void ssd_passC_unit(const Args& a, LAS unsigned char* lds, int unit, int tid, int w4, int lane, LAS unsigned* bcnt, unsigned& btarget) {
;     ...
;     const bf16_t* zrow = (const bf16_t*)(a.ws + WS_PROJ) + (size_t)row * NPROJ + g * 256 + h4 * 64;
;     u32x2 zq[2][4];
; #pragma unroll
;     for (int pt = 0; pt < 2; ++pt)
; #pragma unroll
;         for (int i = 0; i < 4; ++i) zq[pt][i] = *(const u32x2*)(zrow + pt * 32 + 8 * i + 4 * hf);
;     bf16x8 cf[8];
; #pragma unroll
;     for (int ks = 0; ks < 8; ++ks) cf[ks] = *(const LAS bf16x8*)(Cn + l * BN_LD + ks * 16 + 8 * hf);
;     f32x16 ya[2]; ya[0] = zero16(); ya[1] = zero16();
;     const bf16_t* hp = (const bf16_t*)(a.ws + WS_SST) + ((size_t)si.slot * 8 + h) * 8192;
; #pragma unroll
;     for (int ks = 0; ks < 8; ++ks) {
; #pragma unroll
;         for (int pt = 0; pt < 2; ++pt) { const bf16x8 af = *(const bf16x8*)(hp + (pt * 32 + r) * 128 + ks * 16 + 8 * hf); ya[pt] = MFMA32(af, cf[ks], ya[pt]); }
;     }
;     { const float e = ecs[l];
; #pragma unroll
;       for (int pt = 0; pt < 2; ++pt)
; #pragma unroll
;           for (int i = 0; i < 16; ++i) ya[pt][i] *= e; }
;     const float csl = cs[l];
; #pragma unroll
;     for (int st = 0; st < 2; ++st) {
;         if (st <= lh) {
;             f32x16 sa = zero16();
; #pragma unroll
;             for (int ks = 0; ks < 8; ++ks) { const bf16x8 af = *(const LAS bf16x8*)(Bn + (st * 32 + r) * BN_LD + ks * 16 + 8 * hf); sa = MFMA32(af, cf[ks], sa); }
; #pragma unroll
;             for (int i = 0; i < 16; ++i) { const int s = st * 32 + (i & 3) + 8 * (i >> 2) + 4 * hf;
;                 const float v = sa[i] * __expf(csl - cs[s]) * dtl[s]; sa[i] = (s <= l) ? v : 0.f; }
.LBB0_840:
	v_or_b32_e32 v108, s16, v212
	v_add_u32_e32 v174, s33, v108
	v_ashrrev_i32_e32 v175, 31, v174
	v_lshlrev_b64 v[0:1], 12, v[174:175]
	v_lshl_add_u64 v[0:1], v[80:81], 0, v[0:1]
	s_movk_i32 s16, 0x110
	global_load_dwordx2 v[192:193], v[0:1], off
	global_load_dwordx2 v[190:191], v[0:1], off offset:16
	global_load_dwordx2 v[188:189], v[0:1], off offset:32
	global_load_dwordx2 v[186:187], v[0:1], off offset:48
	global_load_dwordx2 v[184:185], v[0:1], off offset:64
	global_load_dwordx2 v[182:183], v[0:1], off offset:80
	global_load_dwordx2 v[180:181], v[0:1], off offset:96
	global_load_dwordx2 v[178:179], v[0:1], off offset:112
	v_mad_u32_u24 v0, v108, s16, v213
	ds_read_b128 v[72:75], v0 offset:55296
	ds_read_b128 v[76:79], v0 offset:55328
	ds_read_b128 v[68:71], v0 offset:55360
	ds_read_b128 v[64:67], v0 offset:55392
	ds_read_b128 v[60:63], v0 offset:55424
	ds_read_b128 v[56:59], v0 offset:55456
	ds_read_b128 v[52:55], v0 offset:55488
	ds_read_b128 v[48:51], v0 offset:55520
	global_load_dwordx4 v[0:3], v[82:83], off
	global_load_dwordx4 v[32:35], v[82:83], off offset:32
	global_load_dwordx4 v[36:39], v[82:83], off offset:64
	global_load_dwordx4 v[40:43], v[82:83], off offset:96
	global_load_dwordx4 v[44:47], v[82:83], off offset:128
	global_load_dwordx4 v[196:199], v[82:83], off offset:160
	global_load_dwordx4 v[86:89], v[82:83], off offset:192
	global_load_dwordx4 v[90:93], v[82:83], off offset:224
	global_load_dwordx4 v[94:97], v[84:85], off offset:32
	v_cmp_le_u32_e32 vcc, v106, v108
	v_add_u32_e32 v155, v222, v223
	v_add_u32_e32 v157, v222, v224
	v_add_u32_e32 v151, v225, v223
	v_add_u32_e32 v153, v225, v224
	v_add_u32_e32 v147, v222, v226
	v_add_u32_e32 v149, v222, v227
	s_waitcnt vmcnt(8) lgkmcnt(7)
	v_mfma_f32_32x32x16_bf16 v[16:31], v[0:3], v[72:75], 0
	global_load_dwordx4 v[0:3], v[84:85], off
	s_waitcnt vmcnt(8) lgkmcnt(6)
	v_mfma_f32_32x32x16_bf16 v[16:31], v[32:35], v[76:79], v[16:31]
	global_load_dwordx4 v[32:35], v[84:85], off offset:64
	s_waitcnt vmcnt(8) lgkmcnt(5)
	v_mfma_f32_32x32x16_bf16 v[16:31], v[36:39], v[68:71], v[16:31]
	global_load_dwordx4 v[36:39], v[84:85], off offset:96
	s_waitcnt vmcnt(8) lgkmcnt(4)
	v_mfma_f32_32x32x16_bf16 v[16:31], v[40:43], v[64:67], v[16:31]
	global_load_dwordx4 v[40:43], v[84:85], off offset:128
	s_waitcnt vmcnt(8) lgkmcnt(3)
	v_mfma_f32_32x32x16_bf16 v[16:31], v[44:47], v[60:63], v[16:31]
	global_load_dwordx4 v[44:47], v[84:85], off offset:160
	s_waitcnt vmcnt(8) lgkmcnt(2)
	v_mfma_f32_32x32x16_bf16 v[16:31], v[196:199], v[56:59], v[16:31]
	global_load_dwordx4 v[196:199], v[84:85], off offset:192
	s_waitcnt vmcnt(8) lgkmcnt(1)
	v_mfma_f32_32x32x16_bf16 v[16:31], v[86:89], v[52:55], v[16:31]
	global_load_dwordx4 v[86:89], v[84:85], off offset:224
	s_waitcnt vmcnt(8) lgkmcnt(0)
	v_mfma_f32_32x32x16_bf16 v[16:31], v[90:93], v[48:51], v[16:31]
	s_waitcnt vmcnt(6)
	v_mfma_f32_32x32x16_bf16 v[0:15], v[0:3], v[72:75], 0
	v_mfma_f32_32x32x16_bf16 v[0:15], v[94:97], v[76:79], v[0:15]
	s_waitcnt vmcnt(5)
	v_mfma_f32_32x32x16_bf16 v[0:15], v[32:35], v[68:71], v[0:15]
	s_waitcnt vmcnt(4)
	v_mfma_f32_32x32x16_bf16 v[0:15], v[36:39], v[64:67], v[0:15]
	s_waitcnt vmcnt(3)
	v_mfma_f32_32x32x16_bf16 v[0:15], v[40:43], v[60:63], v[0:15]
	s_waitcnt vmcnt(2)
	v_mfma_f32_32x32x16_bf16 v[0:15], v[44:47], v[56:59], v[0:15]
	s_waitcnt vmcnt(1)
	v_mfma_f32_32x32x16_bf16 v[0:15], v[196:199], v[52:55], v[0:15]
	s_waitcnt vmcnt(0)
	v_mfma_f32_32x32x16_bf16 v[0:15], v[86:89], v[48:51], v[0:15]
	v_lshl_add_u32 v32, v108, 2, s93
	ds_read2st64_b32 v[194:195], v32 offset1:8
	ds_read_b128 v[32:35], v247 offset:36864
	ds_read_b128 v[196:199], v247 offset:36896
	s_waitcnt lgkmcnt(1)
	v_mfma_f32_32x32x16_bf16 v[32:47], v[32:35], v[72:75], 0
	s_waitcnt lgkmcnt(0)
	v_mfma_f32_32x32x16_bf16 v[32:47], v[196:199], v[76:79], v[32:47]
	ds_read_b128 v[196:199], v247 offset:36928
	s_waitcnt lgkmcnt(0)
	v_mfma_f32_32x32x16_bf16 v[32:47], v[196:199], v[68:71], v[32:47]
	ds_read_b128 v[196:199], v247 offset:36960
	s_waitcnt lgkmcnt(0)
	v_mfma_f32_32x32x16_bf16 v[32:47], v[196:199], v[64:67], v[32:47]
	ds_read_b128 v[196:199], v247 offset:36992
	s_waitcnt lgkmcnt(0)
	v_mfma_f32_32x32x16_bf16 v[32:47], v[196:199], v[60:63], v[32:47]
	ds_read_b128 v[196:199], v247 offset:37024
	s_waitcnt lgkmcnt(0)
	v_mfma_f32_32x32x16_bf16 v[32:47], v[196:199], v[56:59], v[32:47]
	ds_read_b128 v[196:199], v247 offset:37056
	s_waitcnt lgkmcnt(0)
	v_mfma_f32_32x32x16_bf16 v[32:47], v[196:199], v[52:55], v[32:47]
	ds_read_b128 v[196:199], v247 offset:37088
	s_waitcnt lgkmcnt(0)
	v_mfma_f32_32x32x16_bf16 v[32:47], v[196:199], v[48:51], v[32:47]
	ds_read2st64_b64 v[196:199], v214 offset1:2
	s_waitcnt lgkmcnt(0)
	v_sub_f32_e32 v143, v194, v196
	v_mul_f32_e32 v143, 0x3fb8aa3b, v143
	v_exp_f32_e32 v143, v143
	s_nop 6
	v_mul_f32_e32 v32, v32, v143
	v_mul_f32_e32 v32, v198, v32
	v_cndmask_b32_e32 v143, 0, v32, vcc
	v_sub_f32_e32 v32, v194, v197
	v_mul_f32_e32 v32, 0x3fb8aa3b, v32
	v_exp_f32_e32 v32, v32
	v_cmp_lt_u32_e32 vcc, v106, v108
	v_mul_f32_e32 v32, v33, v32
	v_mul_f32_e32 v32, v199, v32
	v_lshl_add_u32 v33, v107, 2, s93
	v_cndmask_b32_e32 v145, 0, v32, vcc
	ds_read_b32 v32, v215
	ds_read_b32 v33, v33
	v_cmp_le_u32_e32 vcc, v110, v108
	s_waitcnt lgkmcnt(1)
	v_sub_f32_e32 v32, v194, v32
	s_waitcnt lgkmcnt(0)
	v_sub_f32_e32 v33, v194, v33
	v_mul_f32_e32 v32, 0x3fb8aa3b, v32
	v_mul_f32_e32 v33, 0x3fb8aa3b, v33
	v_exp_f32_e32 v32, v32
	v_exp_f32_e32 v33, v33
	s_nop 0
	v_pk_mul_f32 v[32:33], v[34:35], v[32:33]
	ds_read_b64 v[34:35], v215 offset:1024
	s_waitcnt lgkmcnt(0)
; #define LAS __attribute__((address_space(3)))
; __device__ __forceinline__ unsigned pk2(float lo, float hi) { f32x2 v; v.x = lo; v.y = hi; return __builtin_bit_cast(unsigned, __builtin_convertvector(v, hwbf2)); }
; #define MFMA32(a, b, c) __builtin_amdgcn_mfma_f32_32x32x16_bf16((a), (b), (c), 0, 0, 0)
; __device__ __forceinline__ f32x16 zero16() { f32x16 z; for (int i = 0; i < 16; ++i) z[i] = 0.f; return z; }
; __device__ __forceinline__ void ssd_passC_unit(const Args& a, LAS unsigned char* lds, int unit, int tid, int w4, int lane, LAS unsigned* bcnt, unsigned& btarget) {
;     ...
;     { const float e = ecs[l];
; #pragma unroll
;       for (int pt = 0; pt < 2; ++pt)
; #pragma unroll
;           for (int i = 0; i < 16; ++i) ya[pt][i] *= e; }
;     const float csl = cs[l];
; #pragma unroll
;     for (int st = 0; st < 2; ++st) {
;         if (st <= lh) {
;             f32x16 sa = zero16();
; #pragma unroll
;             for (int ks = 0; ks < 8; ++ks) { const bf16x8 af = *(const LAS bf16x8*)(Bn + (st * 32 + r) * BN_LD + ks * 16 + 8 * hf); sa = MFMA32(af, cf[ks], sa); }
; #pragma unroll
;             for (int i = 0; i < 16; ++i) { const int s = st * 32 + (i & 3) + 8 * (i >> 2) + 4 * hf;
;                 const float v = sa[i] * __expf(csl - cs[s]) * dtl[s]; sa[i] = (s <= l) ? v : 0.f; }
; #pragma unroll
;             for (int k2 = 0; k2 < 2; ++k2) {
;                 u32x4 gp; gp.x = pk2(sa[8 * k2 + 0], sa[8 * k2 + 1]); gp.y = pk2(sa[8 * k2 + 2], sa[8 * k2 + 3]); gp.z = pk2(sa[8 * k2 + 4], sa[8 * k2 + 5]); gp.w = pk2(sa[8 * k2 + 6], sa[8 * k2 + 7]);
;                 const bf16x8 gf = __builtin_bit_cast(bf16x8, gp);
; #pragma unroll
;                 for (int pt = 0; pt < 2; ++pt) {
;                     const LAS bf16_t* xr = XT + (pt * 32 + r) * XT_LD + 4 * hf; const int swz = (pt * 4 + (r >> 3)) & 7;
;                     const u32x2 lo = *(const LAS u32x2*)(xr + (((st * 4 + 2 * k2) ^ swz) << 3)), hi = *(const LAS u32x2*)(xr + (((st * 4 + 2 * k2 + 1) ^ swz) << 3));
;                     u32x4 xa; xa.x = lo.x; xa.y = lo.y; xa.z = hi.x; xa.w = hi.y;
;                     ya[pt] = MFMA32(__builtin_bit_cast(bf16x8, xa), gf, ya[pt]);
;                 }
	v_pk_mul_f32 v[32:33], v[34:35], v[32:33]
	v_lshl_add_u32 v35, v111, 2, s93
	ds_read_b32 v34, v216
	ds_read_b32 v35, v35
	v_cvt_pk_bf16_f32 v32, v32, v33
	v_cndmask_b32_e32 v33, 0, v32, vcc
	v_lshrrev_b32_e32 v32, 16, v32
	s_waitcnt lgkmcnt(1)
	v_sub_f32_e32 v34, v194, v34
	s_waitcnt lgkmcnt(0)
	v_sub_f32_e32 v35, v194, v35
	v_mul_f32_e32 v34, 0x3fb8aa3b, v34
	v_mul_f32_e32 v35, 0x3fb8aa3b, v35
	v_exp_f32_e32 v34, v34
	v_exp_f32_e32 v35, v35
	v_cmp_le_u32_e32 vcc, v107, v108
	v_pk_mul_f32 v[34:35], v[36:37], v[34:35]
	ds_read_b64 v[36:37], v216 offset:1024
	v_cndmask_b32_e32 v32, 0, v32, vcc
	v_cmp_le_u32_e32 vcc, v112, v108
	s_waitcnt lgkmcnt(0)
	v_pk_mul_f32 v[34:35], v[36:37], v[34:35]
	v_lshl_add_u32 v37, v113, 2, s93
	ds_read_b32 v36, v217
	ds_read_b32 v37, v37
	s_waitcnt lgkmcnt(1)
	v_sub_f32_e32 v36, v194, v36
	s_waitcnt lgkmcnt(0)
	v_sub_f32_e32 v37, v194, v37
	v_mul_f32_e32 v36, 0x3fb8aa3b, v36
	v_mul_f32_e32 v37, 0x3fb8aa3b, v37
	v_exp_f32_e32 v36, v36
	v_exp_f32_e32 v37, v37
	s_nop 0
	v_pk_mul_f32 v[36:37], v[38:39], v[36:37]
	ds_read_b64 v[38:39], v217 offset:1024
	s_waitcnt lgkmcnt(0)
	v_pk_mul_f32 v[36:37], v[38:39], v[36:37]
	v_lshl_add_u32 v39, v115, 2, s93
	ds_read_b32 v38, v218
	ds_read_b32 v39, v39
	s_waitcnt lgkmcnt(1)
	v_sub_f32_e32 v38, v194, v38
	s_waitcnt lgkmcnt(0)
	v_sub_f32_e32 v39, v194, v39
	v_mul_f32_e32 v38, 0x3fb8aa3b, v38
	v_mul_f32_e32 v39, 0x3fb8aa3b, v39
	v_exp_f32_e32 v38, v38
	v_exp_f32_e32 v39, v39
	s_nop 0
	v_pk_mul_f32 v[38:39], v[40:41], v[38:39]
	ds_read_b64 v[40:41], v218 offset:1024
	s_waitcnt lgkmcnt(0)
	v_pk_mul_f32 v[38:39], v[40:41], v[38:39]
	v_lshl_add_u32 v41, v117, 2, s93
	ds_read_b32 v40, v219
	ds_read_b32 v41, v41
	s_waitcnt lgkmcnt(1)
	v_sub_f32_e32 v40, v194, v40
	s_waitcnt lgkmcnt(0)
	v_sub_f32_e32 v41, v194, v41
	v_mul_f32_e32 v40, 0x3fb8aa3b, v40
	v_mul_f32_e32 v41, 0x3fb8aa3b, v41
	v_exp_f32_e32 v40, v40
	v_exp_f32_e32 v41, v41
	s_nop 0
	v_pk_mul_f32 v[40:41], v[42:43], v[40:41]
	ds_read_b64 v[42:43], v219 offset:1024
	s_waitcnt lgkmcnt(0)
	v_pk_mul_f32 v[40:41], v[42:43], v[40:41]
	v_lshl_add_u32 v43, v119, 2, s93
	ds_read_b32 v42, v220
	ds_read_b32 v43, v43
	s_waitcnt lgkmcnt(1)
	v_sub_f32_e32 v42, v194, v42
	s_waitcnt lgkmcnt(0)
	v_sub_f32_e32 v43, v194, v43
	v_mul_f32_e32 v42, 0x3fb8aa3b, v42
	v_mul_f32_e32 v43, 0x3fb8aa3b, v43
	v_exp_f32_e32 v42, v42
	v_exp_f32_e32 v43, v43
	s_nop 0
	v_pk_mul_f32 v[42:43], v[44:45], v[42:43]
	ds_read_b64 v[44:45], v220 offset:1024
	s_waitcnt lgkmcnt(0)
	v_pk_mul_f32 v[42:43], v[44:45], v[42:43]
	v_lshl_add_u32 v45, v121, 2, s93
	ds_read_b32 v44, v221
	ds_read_b32 v45, v45
	s_waitcnt lgkmcnt(1)
	v_sub_f32_e32 v44, v194, v44
	s_waitcnt lgkmcnt(0)
	v_sub_f32_e32 v45, v194, v45
	v_mul_f32_e32 v44, 0x3fb8aa3b, v44
	v_mul_f32_e32 v45, 0x3fb8aa3b, v45
	v_exp_f32_e32 v44, v44
	v_exp_f32_e32 v45, v45
	s_nop 0
	v_pk_mul_f32 v[44:45], v[46:47], v[44:45]
	ds_read_b64 v[46:47], v221 offset:1024
	s_waitcnt lgkmcnt(0)
	v_pk_mul_f32 v[196:197], v[46:47], v[44:45]
	v_perm_b32 v45, v32, v33, s27
	v_cvt_pk_bf16_f32 v32, v34, v35
	v_cndmask_b32_e32 v33, 0, v32, vcc
	v_lshrrev_b32_e32 v32, 16, v32
	v_cmp_le_u32_e32 vcc, v111, v108
	ds_read_b64 v[34:35], v157
	v_cvt_pk_bf16_f32 v44, v143, v145
	v_cndmask_b32_e32 v32, 0, v32, vcc
	v_perm_b32 v46, v32, v33, s27
	v_cvt_pk_bf16_f32 v32, v36, v37
	v_cmp_le_u32_e32 vcc, v114, v108
	v_mov_b32_e32 v36, v195
	v_pk_mul_f32 v[30:31], v[30:31], v[36:37] op_sel_hi:[1,0]
	v_cndmask_b32_e32 v33, 0, v32, vcc
	v_lshrrev_b32_e32 v32, 16, v32
	v_cmp_le_u32_e32 vcc, v113, v108
	v_pk_mul_f32 v[28:29], v[28:29], v[36:37] op_sel_hi:[1,0]
	v_pk_mul_f32 v[26:27], v[26:27], v[36:37] op_sel_hi:[1,0]
	v_cndmask_b32_e32 v32, 0, v32, vcc
	v_perm_b32 v47, v32, v33, s27
	ds_read_b64 v[32:33], v155
	v_pk_mul_f32 v[24:25], v[24:25], v[36:37] op_sel_hi:[1,0]
	v_pk_mul_f32 v[22:23], v[22:23], v[36:37] op_sel_hi:[1,0]
	v_pk_mul_f32 v[20:21], v[20:21], v[36:37] op_sel_hi:[1,0]
	v_pk_mul_f32 v[18:19], v[18:19], v[36:37] op_sel_hi:[1,0]
	v_pk_mul_f32 v[16:17], v[16:17], v[36:37] op_sel_hi:[1,0]
	v_pk_mul_f32 v[14:15], v[14:15], v[36:37] op_sel_hi:[1,0]
	v_pk_mul_f32 v[12:13], v[12:13], v[36:37] op_sel_hi:[1,0]
	s_waitcnt lgkmcnt(0)
	v_mfma_f32_32x32x16_bf16 v[16:31], v[32:35], v[44:47], v[16:31]
	ds_read_b64 v[32:33], v151 offset:64
	ds_read_b64 v[34:35], v153 offset:64
	v_mul_f32_e64 v10, v10, v36
	v_mul_f32_e64 v11, v11, v36
	v_mul_f32_e64 v8, v8, v36
	v_mul_f32_e64 v9, v9, v36
	v_pk_mul_f32 v[6:7], v[6:7], v[36:37] op_sel_hi:[1,0]
	v_pk_mul_f32 v[4:5], v[4:5], v[36:37] op_sel_hi:[1,0]
	v_pk_mul_f32 v[2:3], v[2:3], v[36:37] op_sel_hi:[1,0]
	v_pk_mul_f32 v[0:1], v[0:1], v[36:37] op_sel_hi:[1,0]
	v_cmp_le_u32_e32 vcc, v116, v108
	v_add_u32_e32 v143, v225, v226
	s_waitcnt lgkmcnt(0)
	v_mfma_f32_32x32x16_bf16 v[0:15], v[32:35], v[44:47], v[0:15]
	v_cvt_pk_bf16_f32 v32, v38, v39
	v_cndmask_b32_e32 v33, 0, v32, vcc
	v_lshrrev_b32_e32 v32, 16, v32
	v_cmp_le_u32_e32 vcc, v115, v108
	ds_read_b64 v[38:39], v149
	v_add_u32_e32 v145, v225, v227
	v_cndmask_b32_e32 v32, 0, v32, vcc
	v_perm_b32 v32, v32, v33, s27
	v_cvt_pk_bf16_f32 v33, v40, v41
	v_cmp_le_u32_e32 vcc, v118, v108
	s_nop 1
	v_cndmask_b32_e32 v34, 0, v33, vcc
	v_lshrrev_b32_e32 v33, 16, v33
	v_cmp_le_u32_e32 vcc, v117, v108
	s_nop 1
	v_cndmask_b32_e32 v33, 0, v33, vcc
	v_perm_b32 v33, v33, v34, s27
	v_cvt_pk_bf16_f32 v34, v42, v43
	v_cmp_le_u32_e32 vcc, v120, v108
	s_nop 1
	v_cndmask_b32_e32 v35, 0, v34, vcc
	v_lshrrev_b32_e32 v34, 16, v34
	v_cmp_le_u32_e32 vcc, v119, v108
	s_nop 1
	v_cndmask_b32_e32 v34, 0, v34, vcc
	v_perm_b32 v34, v34, v35, s27
	v_cvt_pk_bf16_f32 v35, v196, v197
	v_cmp_le_u32_e32 vcc, v122, v108
	s_nop 1
	v_cndmask_b32_e32 v36, 0, v35, vcc
	v_lshrrev_b32_e32 v35, 16, v35
	v_cmp_le_u32_e32 vcc, v121, v108
	s_nop 1
	v_cndmask_b32_e32 v35, 0, v35, vcc
	v_perm_b32 v35, v35, v36, s27
	ds_read_b64 v[36:37], v147
	s_and_b64 vcc, exec, s[0:1]
	s_waitcnt lgkmcnt(0)
	v_mfma_f32_32x32x16_bf16 v[16:31], v[36:39], v[32:35], v[16:31]
	ds_read_b64 v[36:37], v143 offset:64
	ds_read_b64 v[38:39], v145 offset:64
	s_waitcnt lgkmcnt(0)
	v_mfma_f32_32x32x16_bf16 v[0:15], v[36:39], v[32:35], v[0:15]
	s_cbranch_vccnz .LBB0_842
; #define LAS __attribute__((address_space(3)))
; __device__ __forceinline__ unsigned pk2(float lo, float hi) { f32x2 v; v.x = lo; v.y = hi; return __builtin_bit_cast(unsigned, __builtin_convertvector(v, hwbf2)); }
; #define MFMA32(a, b, c) __builtin_amdgcn_mfma_f32_32x32x16_bf16((a), (b), (c), 0, 0, 0)
; __device__ __forceinline__ f32x16 zero16() { f32x16 z; for (int i = 0; i < 16; ++i) z[i] = 0.f; return z; }
; __device__ __forceinline__ void ssd_passC_unit(const Args& a, LAS unsigned char* lds, int unit, int tid, int w4, int lane, LAS unsigned* bcnt, unsigned& btarget) {
;     ...
;         if (st <= lh) {
;             f32x16 sa = zero16();
; #pragma unroll
;             for (int ks = 0; ks < 8; ++ks) { const bf16x8 af = *(const LAS bf16x8*)(Bn + (st * 32 + r) * BN_LD + ks * 16 + 8 * hf); sa = MFMA32(af, cf[ks], sa); }
; #pragma unroll
;             for (int i = 0; i < 16; ++i) { const int s = st * 32 + (i & 3) + 8 * (i >> 2) + 4 * hf;
;                 const float v = sa[i] * __expf(csl - cs[s]) * dtl[s]; sa[i] = (s <= l) ? v : 0.f; }
; #pragma unroll
;             for (int k2 = 0; k2 < 2; ++k2) {
;                 u32x4 gp; gp.x = pk2(sa[8 * k2 + 0], sa[8 * k2 + 1]); gp.y = pk2(sa[8 * k2 + 2], sa[8 * k2 + 3]); gp.z = pk2(sa[8 * k2 + 4], sa[8 * k2 + 5]); gp.w = pk2(sa[8 * k2 + 6], sa[8 * k2 + 7]);
;                 const bf16x8 gf = __builtin_bit_cast(bf16x8, gp);
; #pragma unroll
;                 for (int pt = 0; pt < 2; ++pt) {
;                     const LAS bf16_t* xr = XT + (pt * 32 + r) * XT_LD + 4 * hf; const int swz = (pt * 4 + (r >> 3)) & 7;
;                     const u32x2 lo = *(const LAS u32x2*)(xr + (((st * 4 + 2 * k2) ^ swz) << 3)), hi = *(const LAS u32x2*)(xr + (((st * 4 + 2 * k2 + 1) ^ swz) << 3));
;                     u32x4 xa; xa.x = lo.x; xa.y = lo.y; xa.z = hi.x; xa.w = hi.y;
;                     ya[pt] = MFMA32(__builtin_bit_cast(bf16x8, xa), gf, ya[pt]);
;                 }
	ds_read_b128 v[32:35], v248 offset:36864
	ds_read_b128 v[196:199], v248 offset:36896
	v_cmp_le_u32_e32 vcc, v124, v108
	s_waitcnt lgkmcnt(1)
	v_mfma_f32_32x32x16_bf16 v[32:47], v[32:35], v[72:75], 0
	ds_read_b128 v[72:75], v248 offset:36928
	s_waitcnt lgkmcnt(1)
	v_mfma_f32_32x32x16_bf16 v[32:47], v[196:199], v[76:79], v[32:47]
	s_waitcnt lgkmcnt(0)
	v_mfma_f32_32x32x16_bf16 v[32:47], v[72:75], v[68:71], v[32:47]
	ds_read_b128 v[68:71], v248 offset:36960
	s_waitcnt lgkmcnt(0)
	v_mfma_f32_32x32x16_bf16 v[32:47], v[68:71], v[64:67], v[32:47]
	ds_read_b128 v[64:67], v248 offset:36992
	s_waitcnt lgkmcnt(0)
	v_mfma_f32_32x32x16_bf16 v[32:47], v[64:67], v[60:63], v[32:47]
	ds_read_b128 v[60:63], v248 offset:37024
	s_waitcnt lgkmcnt(0)
	v_mfma_f32_32x32x16_bf16 v[32:47], v[60:63], v[56:59], v[32:47]
	ds_read_b128 v[56:59], v248 offset:37056
	s_waitcnt lgkmcnt(0)
	v_mfma_f32_32x32x16_bf16 v[32:47], v[56:59], v[52:55], v[32:47]
	ds_read_b128 v[52:55], v248 offset:37088
	s_waitcnt lgkmcnt(0)
	v_mfma_f32_32x32x16_bf16 v[32:47], v[52:55], v[48:51], v[32:47]
	v_lshl_add_u32 v49, v123, 2, s93
	ds_read_b32 v48, v228
	ds_read_b32 v49, v49
	s_waitcnt lgkmcnt(1)
	v_sub_f32_e32 v48, v194, v48
	s_waitcnt lgkmcnt(0)
	v_sub_f32_e32 v49, v194, v49
	v_mul_f32_e32 v48, 0x3fb8aa3b, v48
	v_mul_f32_e32 v49, 0x3fb8aa3b, v49
	v_exp_f32_e32 v48, v48
	v_exp_f32_e32 v49, v49
	s_nop 0
	v_pk_mul_f32 v[32:33], v[32:33], v[48:49]
	ds_read_b64 v[48:49], v228 offset:1024
	s_waitcnt lgkmcnt(0)
	v_pk_mul_f32 v[32:33], v[48:49], v[32:33]
	v_lshl_add_u32 v49, v125, 2, s93
	ds_read_b32 v48, v229
	ds_read_b32 v49, v49
	v_cvt_pk_bf16_f32 v32, v32, v33
	v_cndmask_b32_e32 v33, 0, v32, vcc
	v_lshrrev_b32_e32 v32, 16, v32
	s_waitcnt lgkmcnt(1)
	v_sub_f32_e32 v48, v194, v48
	s_waitcnt lgkmcnt(0)
	v_sub_f32_e32 v49, v194, v49
	v_mul_f32_e32 v48, 0x3fb8aa3b, v48
	v_mul_f32_e32 v49, 0x3fb8aa3b, v49
	v_exp_f32_e32 v48, v48
	v_exp_f32_e32 v49, v49
	v_cmp_le_u32_e32 vcc, v123, v108
	v_pk_mul_f32 v[34:35], v[34:35], v[48:49]
	ds_read_b64 v[48:49], v229 offset:1024
	v_cndmask_b32_e32 v32, 0, v32, vcc
	v_perm_b32 v32, v32, v33, s27
	v_cmp_le_u32_e32 vcc, v126, v108
	s_waitcnt lgkmcnt(0)
	v_pk_mul_f32 v[34:35], v[48:49], v[34:35]
	v_lshl_add_u32 v49, v127, 2, s93
	ds_read_b32 v48, v230
	ds_read_b32 v49, v49
	v_cvt_pk_bf16_f32 v33, v34, v35
	v_cndmask_b32_e32 v34, 0, v33, vcc
	v_lshrrev_b32_e32 v33, 16, v33
	s_waitcnt lgkmcnt(1)
	v_sub_f32_e32 v48, v194, v48
	s_waitcnt lgkmcnt(0)
	v_sub_f32_e32 v49, v194, v49
	v_mul_f32_e32 v48, 0x3fb8aa3b, v48
	v_mul_f32_e32 v49, 0x3fb8aa3b, v49
	v_exp_f32_e32 v48, v48
	v_exp_f32_e32 v49, v49
	v_cmp_le_u32_e32 vcc, v125, v108
	v_pk_mul_f32 v[36:37], v[36:37], v[48:49]
	ds_read_b64 v[48:49], v230 offset:1024
	v_cndmask_b32_e32 v33, 0, v33, vcc
	v_perm_b32 v33, v33, v34, s27
	v_cmp_le_u32_e32 vcc, v128, v108
	s_waitcnt lgkmcnt(0)
	v_pk_mul_f32 v[48:49], v[48:49], v[36:37]
	ds_read_b32 v36, v231
	ds_read_b32 v37, v232
	v_cvt_pk_bf16_f32 v34, v48, v49
	v_cndmask_b32_e32 v35, 0, v34, vcc
	v_lshrrev_b32_e32 v34, 16, v34
	s_waitcnt lgkmcnt(1)
	v_sub_f32_e32 v36, v194, v36
	s_waitcnt lgkmcnt(0)
	v_sub_f32_e32 v37, v194, v37
	v_mul_f32_e32 v36, 0x3fb8aa3b, v36
	v_mul_f32_e32 v37, 0x3fb8aa3b, v37
	v_exp_f32_e32 v36, v36
	v_exp_f32_e32 v37, v37
	v_cmp_le_u32_e32 vcc, v127, v108
	v_pk_mul_f32 v[36:37], v[38:39], v[36:37]
	ds_read_b64 v[38:39], v231 offset:1024
	v_cndmask_b32_e32 v34, 0, v34, vcc
	v_perm_b32 v34, v34, v35, s27
	v_cmp_le_u32_e32 vcc, v130, v108
	s_waitcnt lgkmcnt(0)
	v_pk_mul_f32 v[38:39], v[38:39], v[36:37]
	ds_read_b32 v36, v233
	ds_read_b32 v37, v234
	v_cvt_pk_bf16_f32 v35, v38, v39
	v_cndmask_b32_e32 v38, 0, v35, vcc
	v_lshrrev_b32_e32 v35, 16, v35
	s_waitcnt lgkmcnt(1)
	v_sub_f32_e32 v36, v194, v36
	s_waitcnt lgkmcnt(0)
	v_sub_f32_e32 v37, v194, v37
	v_mul_f32_e32 v36, 0x3fb8aa3b, v36
	v_mul_f32_e32 v37, 0x3fb8aa3b, v37
	v_exp_f32_e32 v36, v36
	v_exp_f32_e32 v37, v37
	v_cmp_le_u32_e32 vcc, v129, v108
	v_pk_mul_f32 v[36:37], v[40:41], v[36:37]
	ds_read_b64 v[40:41], v233 offset:1024
	v_cndmask_b32_e32 v35, 0, v35, vcc
	v_perm_b32 v35, v35, v38, s27
	v_cmp_le_u32_e32 vcc, v132, v108
	s_waitcnt lgkmcnt(0)
	v_pk_mul_f32 v[36:37], v[40:41], v[36:37]
	ds_read_b32 v40, v235
	ds_read_b32 v41, v236
	s_waitcnt lgkmcnt(1)
	v_sub_f32_e32 v40, v194, v40
	s_waitcnt lgkmcnt(0)
	v_sub_f32_e32 v41, v194, v41
	v_mul_f32_e32 v40, 0x3fb8aa3b, v40
	v_mul_f32_e32 v41, 0x3fb8aa3b, v41
	v_exp_f32_e32 v40, v40
	v_exp_f32_e32 v41, v41
	s_nop 0
	v_pk_mul_f32 v[40:41], v[42:43], v[40:41]
	ds_read_b64 v[42:43], v235 offset:1024
	s_waitcnt lgkmcnt(0)
	v_pk_mul_f32 v[40:41], v[42:43], v[40:41]
	ds_read_b32 v42, v237
	ds_read_b32 v43, v238
	s_waitcnt lgkmcnt(1)
	v_sub_f32_e32 v42, v194, v42
	s_waitcnt lgkmcnt(0)
	v_sub_f32_e32 v43, v194, v43
	v_mul_f32_e32 v42, 0x3fb8aa3b, v42
	v_mul_f32_e32 v43, 0x3fb8aa3b, v43
	v_exp_f32_e32 v42, v42
	v_exp_f32_e32 v43, v43
	s_nop 0
	v_pk_mul_f32 v[42:43], v[44:45], v[42:43]
	ds_read_b64 v[44:45], v237 offset:1024
	s_waitcnt lgkmcnt(0)
	v_pk_mul_f32 v[42:43], v[44:45], v[42:43]
	ds_read_b32 v44, v239
	ds_read_b32 v45, v240
	s_waitcnt lgkmcnt(1)
	v_sub_f32_e32 v44, v194, v44
	s_waitcnt lgkmcnt(0)
	v_sub_f32_e32 v45, v194, v45
	v_mul_f32_e32 v44, 0x3fb8aa3b, v44
	v_mul_f32_e32 v45, 0x3fb8aa3b, v45
	v_exp_f32_e32 v44, v44
	v_exp_f32_e32 v45, v45
	s_nop 0
	v_pk_mul_f32 v[44:45], v[46:47], v[44:45]
	ds_read_b64 v[46:47], v239 offset:1024
	s_waitcnt lgkmcnt(0)
	v_pk_mul_f32 v[44:45], v[46:47], v[44:45]
	ds_read_b64 v[46:47], v155 offset:64
	ds_read_b64 v[48:49], v157 offset:64
	s_waitcnt lgkmcnt(0)
; #define LAS __attribute__((address_space(3)))
; __device__ __forceinline__ float bf2f(unsigned v) { return __uint_as_float(v << 16); }
; __device__ __forceinline__ float silu_f(float v) { return v * __builtin_amdgcn_rcpf(1.f + __builtin_amdgcn_exp2f(-1.4426950409f * v)); }
; #define MFMA32(a, b, c) __builtin_amdgcn_mfma_f32_32x32x16_bf16((a), (b), (c), 0, 0, 0)
; __device__ __forceinline__ void ssd_passC_unit(const Args& a, LAS unsigned char* lds, int unit, int tid, int w4, int lane, LAS unsigned* bcnt, unsigned& btarget) {
;     ...
;                     const u32x2 lo = *(const LAS u32x2*)(xr + (((st * 4 + 2 * k2) ^ swz) << 3)), hi = *(const LAS u32x2*)(xr + (((st * 4 + 2 * k2 + 1) ^ swz) << 3));
;                     u32x4 xa; xa.x = lo.x; xa.y = lo.y; xa.z = hi.x; xa.w = hi.y;
;                     ya[pt] = MFMA32(__builtin_bit_cast(bf16x8, xa), gf, ya[pt]);
;                 }
;             }
;         }
;     }
;     const float Dh = a.in[I_SSDD][h];
;     float ssq = 0.f;
; #pragma unroll
;     for (int pt = 0; pt < 2; ++pt)
; #pragma unroll
;         for (int i = 0; i < 4; ++i) {
;             const int p0 = pt * 32 + 8 * i + 4 * hf;
;             const u32x2 zz = zq[pt][i];
;             const float zv[4] = {bf2f(zz.x & 0xffff), bf2f(zz.x >> 16), bf2f(zz.y & 0xffff), bf2f(zz.y >> 16)};
; #pragma unroll
;             for (int j = 0; j < 4; ++j) { const float xv = bf2f(XT[(p0 + j) * XT_LD + ((((l >> 3) ^ ((pt * 4 + i) & 7)) << 3) | (l & 7))]); const float y = (ya[pt][4 * i + j] + Dh * xv) * silu_f(zv[j]); ya[pt][4 * i + j] = y; ssq += y * y; }
;         }
	v_mfma_f32_32x32x16_bf16 v[16:31], v[46:49], v[32:35], v[16:31]
	ds_read_b64 v[46:47], v151
	ds_read_b64 v[48:49], v153
	s_waitcnt lgkmcnt(0)
	v_mfma_f32_32x32x16_bf16 v[0:15], v[46:49], v[32:35], v[0:15]
	v_cvt_pk_bf16_f32 v32, v36, v37
	v_cndmask_b32_e32 v33, 0, v32, vcc
	v_lshrrev_b32_e32 v32, 16, v32
	v_cmp_le_u32_e32 vcc, v131, v108
	s_nop 1
	v_cndmask_b32_e32 v32, 0, v32, vcc
	v_perm_b32 v32, v32, v33, s27
	v_cvt_pk_bf16_f32 v33, v40, v41
	v_cmp_le_u32_e32 vcc, v134, v108
	s_nop 1
	v_cndmask_b32_e32 v34, 0, v33, vcc
	v_lshrrev_b32_e32 v33, 16, v33
	v_cmp_le_u32_e32 vcc, v133, v108
	s_nop 1
	v_cndmask_b32_e32 v33, 0, v33, vcc
	v_perm_b32 v33, v33, v34, s27
	v_cvt_pk_bf16_f32 v34, v42, v43
	v_cmp_le_u32_e32 vcc, v136, v108
	s_nop 1
	v_cndmask_b32_e32 v35, 0, v34, vcc
	v_lshrrev_b32_e32 v34, 16, v34
	v_cmp_le_u32_e32 vcc, v135, v108
	s_nop 1
	v_cndmask_b32_e32 v34, 0, v34, vcc
	v_perm_b32 v34, v34, v35, s27
	v_cvt_pk_bf16_f32 v35, v44, v45
	v_cmp_le_u32_e32 vcc, v138, v108
	s_nop 1
	v_cndmask_b32_e32 v36, 0, v35, vcc
	v_lshrrev_b32_e32 v35, 16, v35
	v_cmp_le_u32_e32 vcc, v137, v108
	s_nop 1
	v_cndmask_b32_e32 v35, 0, v35, vcc
	v_perm_b32 v35, v35, v36, s27
	ds_read_b64 v[36:37], v147 offset:64
	ds_read_b64 v[38:39], v149 offset:64
	s_waitcnt lgkmcnt(0)
	v_mfma_f32_32x32x16_bf16 v[16:31], v[36:39], v[32:35], v[16:31]
	ds_read_b64 v[36:37], v143
	ds_read_b64 v[38:39], v145
	s_waitcnt lgkmcnt(0)
	v_mfma_f32_32x32x16_bf16 v[0:15], v[36:39], v[32:35], v[0:15]
.LBB0_842:
	global_load_dword v38, v109, s[20:21]
	v_and_b32_e32 v32, 56, v108
	v_lshl_add_u32 v39, v32, 1, v241
	ds_read_u16 v35, v39
	ds_read_u16 v36, v39 offset:144
	v_lshlrev_b32_e32 v32, 16, v192
	v_and_b32_e32 v33, 0xffff0000, v192
	v_mul_f32_e32 v34, 0xbfb8aa3b, v32
	v_exp_f32_e32 v34, v34
	s_waitcnt lgkmcnt(0)
	v_lshlrev_b32_e32 v37, 16, v36
	v_lshlrev_b32_e32 v36, 16, v35
	v_mul_f32_e32 v35, 0xbfb8aa3b, v33
	v_exp_f32_e32 v35, v35
	v_add_f32_e32 v34, 1.0, v34
	v_rcp_f32_e32 v34, v34
	v_add_f32_e32 v35, 1.0, v35
	v_rcp_f32_e32 v35, v35
	s_waitcnt vmcnt(0)
	v_pk_fma_f32 v[16:17], v[38:39], v[36:37], v[16:17] op_sel_hi:[0,1,1]
	v_pk_mul_f32 v[32:33], v[34:35], v[32:33]
	ds_read_u16 v35, v39 offset:288
	ds_read_u16 v39, v39 offset:432
	v_pk_mul_f32 v[32:33], v[32:33], v[16:17]
	v_lshlrev_b32_e32 v16, 16, v193
	v_and_b32_e32 v17, 0xffff0000, v193
	v_mul_f32_e32 v34, 0xbfb8aa3b, v16
	s_waitcnt lgkmcnt(1)
	v_lshlrev_b32_e32 v40, 16, v35
	v_mul_f32_e32 v35, 0xbfb8aa3b, v17
	v_exp_f32_e32 v34, v34
	v_exp_f32_e32 v35, v35
	s_waitcnt lgkmcnt(0)
	v_lshlrev_b32_e32 v41, 16, v39
	v_pk_fma_f32 v[18:19], v[38:39], v[40:41], v[18:19] op_sel_hi:[0,1,1]
	v_add_f32_e32 v34, 1.0, v34
	v_add_f32_e32 v35, 1.0, v35
	v_rcp_f32_e32 v34, v34
	v_rcp_f32_e32 v35, v35
	v_pk_mul_f32 v[36:37], v[32:33], v[32:33]
	v_pk_mul_f32 v[16:17], v[34:35], v[16:17]
	s_nop 0
	v_pk_mul_f32 v[34:35], v[16:17], v[18:19]
	v_bitop3_b32 v16, v108, 8, 56 bitop3:0x6c
	v_lshl_add_u32 v39, v16, 1, v241
	ds_read_u16 v19, v39 offset:1152
	ds_read_u16 v42, v39 offset:1296
	v_lshlrev_b32_e32 v16, 16, v190
	v_and_b32_e32 v17, 0xffff0000, v190
	v_mul_f32_e32 v18, 0xbfb8aa3b, v16
	v_exp_f32_e32 v18, v18
	s_waitcnt lgkmcnt(0)
	v_lshlrev_b32_e32 v43, 16, v42
	v_lshlrev_b32_e32 v42, 16, v19
	v_mul_f32_e32 v19, 0xbfb8aa3b, v17
	v_exp_f32_e32 v19, v19
	v_add_f32_e32 v18, 1.0, v18
	v_rcp_f32_e32 v18, v18
	v_pk_fma_f32 v[20:21], v[38:39], v[42:43], v[20:21] op_sel_hi:[0,1,1]
	v_add_f32_e32 v19, 1.0, v19
	v_rcp_f32_e32 v19, v19
	v_pk_mul_f32 v[40:41], v[34:35], v[34:35]
	v_add_f32_e32 v36, v36, v37
	v_add_f32_e32 v36, v36, v40
	v_pk_mul_f32 v[16:17], v[18:19], v[16:17]
	v_lshlrev_b32_e32 v18, 16, v191
	v_pk_mul_f32 v[16:17], v[16:17], v[20:21]
	ds_read_u16 v21, v39 offset:1440
	ds_read_u16 v39, v39 offset:1584
	v_and_b32_e32 v19, 0xffff0000, v191
	v_mul_f32_e32 v20, 0xbfb8aa3b, v18
	v_exp_f32_e32 v20, v20
	s_waitcnt lgkmcnt(1)
	v_lshlrev_b32_e32 v44, 16, v21
	v_mul_f32_e32 v21, 0xbfb8aa3b, v19
	v_exp_f32_e32 v21, v21
	v_add_f32_e32 v20, 1.0, v20
	v_rcp_f32_e32 v20, v20
	s_waitcnt lgkmcnt(0)
	v_lshlrev_b32_e32 v45, 16, v39
	v_add_f32_e32 v21, 1.0, v21
	v_rcp_f32_e32 v21, v21
	v_pk_fma_f32 v[22:23], v[38:39], v[44:45], v[22:23] op_sel_hi:[0,1,1]
	v_pk_mul_f32 v[42:43], v[16:17], v[16:17]
	v_add_f32_e32 v36, v36, v41
	v_pk_mul_f32 v[18:19], v[20:21], v[18:19]
	v_bitop3_b32 v20, v108, 16, 56 bitop3:0x6c
	v_lshl_add_u32 v39, v20, 1, v241
	v_pk_mul_f32 v[18:19], v[18:19], v[22:23]
	ds_read_u16 v23, v39 offset:2304
	ds_read_u16 v46, v39 offset:2448
	v_lshlrev_b32_e32 v20, 16, v188
	v_and_b32_e32 v21, 0xffff0000, v188
	v_mul_f32_e32 v22, 0xbfb8aa3b, v20
	v_exp_f32_e32 v22, v22
	s_waitcnt lgkmcnt(0)
	v_lshlrev_b32_e32 v47, 16, v46
	v_lshlrev_b32_e32 v46, 16, v23
	v_mul_f32_e32 v23, 0xbfb8aa3b, v21
	v_exp_f32_e32 v23, v23
	v_add_f32_e32 v22, 1.0, v22
	v_rcp_f32_e32 v22, v22
	v_pk_fma_f32 v[24:25], v[38:39], v[46:47], v[24:25] op_sel_hi:[0,1,1]
	v_add_f32_e32 v23, 1.0, v23
	v_rcp_f32_e32 v23, v23
	v_add_f32_e32 v36, v36, v42
	v_pk_mul_f32 v[44:45], v[18:19], v[18:19]
	v_add_f32_e32 v36, v36, v43
	v_pk_mul_f32 v[20:21], v[22:23], v[20:21]
	v_lshlrev_b32_e32 v22, 16, v189
	v_pk_mul_f32 v[20:21], v[20:21], v[24:25]
	ds_read_u16 v25, v39 offset:2592
	ds_read_u16 v39, v39 offset:2736
	v_and_b32_e32 v23, 0xffff0000, v189
	v_mul_f32_e32 v24, 0xbfb8aa3b, v22
	v_exp_f32_e32 v24, v24
	s_waitcnt lgkmcnt(1)
	v_lshlrev_b32_e32 v48, 16, v25
	v_mul_f32_e32 v25, 0xbfb8aa3b, v23
	v_exp_f32_e32 v25, v25
	v_add_f32_e32 v24, 1.0, v24
	v_rcp_f32_e32 v24, v24
	s_waitcnt lgkmcnt(0)
; __device__ __forceinline__ float bf2f(unsigned v) { return __uint_as_float(v << 16); }
; __device__ __forceinline__ float silu_f(float v) { return v * __builtin_amdgcn_rcpf(1.f + __builtin_amdgcn_exp2f(-1.4426950409f * v)); }
; __device__ __forceinline__ void ssd_passC_unit(const Args& a, LAS unsigned char* lds, int unit, int tid, int w4, int lane, LAS unsigned* bcnt, unsigned& btarget) {
;     ...
;     for (int pt = 0; pt < 2; ++pt)
; #pragma unroll
;         for (int i = 0; i < 4; ++i) {
;             const int p0 = pt * 32 + 8 * i + 4 * hf;
;             const u32x2 zz = zq[pt][i];
;             const float zv[4] = {bf2f(zz.x & 0xffff), bf2f(zz.x >> 16), bf2f(zz.y & 0xffff), bf2f(zz.y >> 16)};
; #pragma unroll
;             for (int j = 0; j < 4; ++j) { const float xv = bf2f(XT[(p0 + j) * XT_LD + ((((l >> 3) ^ ((pt * 4 + i) & 7)) << 3) | (l & 7))]); const float y = (ya[pt][4 * i + j] + Dh * xv) * silu_f(zv[j]); ya[pt][4 * i + j] = y; ssq += y * y; }
;         }
	v_lshlrev_b32_e32 v49, 16, v39
	v_add_f32_e32 v25, 1.0, v25
	v_rcp_f32_e32 v25, v25
	v_pk_fma_f32 v[26:27], v[38:39], v[48:49], v[26:27] op_sel_hi:[0,1,1]
	v_add_f32_e32 v36, v36, v44
	v_pk_mul_f32 v[46:47], v[20:21], v[20:21]
	v_pk_mul_f32 v[22:23], v[24:25], v[22:23]
	v_bitop3_b32 v24, v108, 24, 56 bitop3:0x6c
	v_lshl_add_u32 v39, v24, 1, v241
	v_pk_mul_f32 v[22:23], v[22:23], v[26:27]
	ds_read_u16 v27, v39 offset:3456
	ds_read_u16 v50, v39 offset:3600
	v_lshlrev_b32_e32 v24, 16, v186
	v_and_b32_e32 v25, 0xffff0000, v186
	v_mul_f32_e32 v26, 0xbfb8aa3b, v24
	v_exp_f32_e32 v26, v26
	s_waitcnt lgkmcnt(0)
	v_lshlrev_b32_e32 v51, 16, v50
	v_lshlrev_b32_e32 v50, 16, v27
	v_mul_f32_e32 v27, 0xbfb8aa3b, v25
	v_exp_f32_e32 v27, v27
	v_add_f32_e32 v26, 1.0, v26
	v_pk_fma_f32 v[28:29], v[38:39], v[50:51], v[28:29] op_sel_hi:[0,1,1]
	ds_read_u16 v51, v39 offset:3744
	ds_read_u16 v39, v39 offset:3888
	v_add_f32_e32 v27, 1.0, v27
	v_rcp_f32_e32 v26, v26
	v_rcp_f32_e32 v27, v27
	s_waitcnt lgkmcnt(1)
	v_lshlrev_b32_e32 v52, 16, v51
	s_waitcnt lgkmcnt(0)
	v_lshlrev_b32_e32 v53, 16, v39
	v_pk_fma_f32 v[30:31], v[38:39], v[52:53], v[30:31] op_sel_hi:[0,1,1]
	v_pk_mul_f32 v[24:25], v[26:27], v[24:25]
	v_and_b32_e32 v27, 0xffff0000, v187
	v_mul_f32_e32 v39, 0xbfb8aa3b, v27
	v_lshlrev_b32_e32 v26, 16, v187
	v_exp_f32_e32 v39, v39
	v_mul_f32_e32 v50, 0xbfb8aa3b, v26
	v_exp_f32_e32 v50, v50
	v_add_f32_e32 v36, v36, v45
	v_add_f32_e32 v39, 1.0, v39
	v_rcp_f32_e32 v51, v39
	v_bitop3_b32 v39, v108, 32, 56 bitop3:0x6c
	v_add_f32_e32 v50, 1.0, v50
	v_lshl_add_u32 v39, v39, 1, v242
	v_rcp_f32_e32 v50, v50
	ds_read_u16 v53, v39
	ds_read_u16 v54, v39 offset:144
	v_add_f32_e32 v36, v36, v46
	v_pk_mul_f32 v[48:49], v[22:23], v[22:23]
	v_pk_mul_f32 v[26:27], v[50:51], v[26:27]
	v_lshlrev_b32_e32 v50, 16, v184
	v_and_b32_e32 v51, 0xffff0000, v184
	v_mul_f32_e32 v52, 0xbfb8aa3b, v50
	s_waitcnt lgkmcnt(0)
	v_lshlrev_b32_e32 v55, 16, v54
	v_lshlrev_b32_e32 v54, 16, v53
	v_mul_f32_e32 v53, 0xbfb8aa3b, v51
	v_exp_f32_e32 v52, v52
	v_exp_f32_e32 v53, v53
	v_pk_fma_f32 v[0:1], v[38:39], v[54:55], v[0:1] op_sel_hi:[0,1,1]
	ds_read_u16 v55, v39 offset:288
	ds_read_u16 v39, v39 offset:432
	v_add_f32_e32 v52, 1.0, v52
	v_add_f32_e32 v53, 1.0, v53
	v_rcp_f32_e32 v52, v52
	v_rcp_f32_e32 v53, v53
	s_waitcnt lgkmcnt(0)
	v_lshlrev_b32_e32 v57, 16, v39
	v_lshlrev_b32_e32 v56, 16, v55
	v_pk_fma_f32 v[2:3], v[38:39], v[56:57], v[2:3] op_sel_hi:[0,1,1]
	v_pk_mul_f32 v[50:51], v[52:53], v[50:51]
	v_and_b32_e32 v53, 0xffff0000, v185
	v_mul_f32_e32 v39, 0xbfb8aa3b, v53
	v_lshlrev_b32_e32 v52, 16, v185
	v_exp_f32_e32 v39, v39
	v_mul_f32_e32 v54, 0xbfb8aa3b, v52
	v_exp_f32_e32 v54, v54
	v_add_f32_e32 v36, v36, v47
	v_add_f32_e32 v39, 1.0, v39
	v_rcp_f32_e32 v55, v39
	v_bitop3_b32 v39, v108, 40, 56 bitop3:0x6c
	v_add_f32_e32 v54, 1.0, v54
	v_lshl_add_u32 v39, v39, 1, v243
	v_rcp_f32_e32 v54, v54
	ds_read_u16 v57, v39
	ds_read_u16 v58, v39 offset:144
	v_pk_mul_f32 v[24:25], v[24:25], v[28:29]
	v_add_f32_e32 v36, v36, v48
	v_pk_mul_f32 v[52:53], v[54:55], v[52:53]
	v_lshlrev_b32_e32 v54, 16, v182
	v_and_b32_e32 v55, 0xffff0000, v182
	v_mul_f32_e32 v56, 0xbfb8aa3b, v54
	s_waitcnt lgkmcnt(0)
	v_lshlrev_b32_e32 v59, 16, v58
	v_lshlrev_b32_e32 v58, 16, v57
	v_mul_f32_e32 v57, 0xbfb8aa3b, v55
	v_exp_f32_e32 v56, v56
	v_exp_f32_e32 v57, v57
	v_pk_fma_f32 v[4:5], v[38:39], v[58:59], v[4:5] op_sel_hi:[0,1,1]
	ds_read_u16 v59, v39 offset:288
	ds_read_u16 v39, v39 offset:432
	v_add_f32_e32 v56, 1.0, v56
	v_add_f32_e32 v57, 1.0, v57
	v_rcp_f32_e32 v56, v56
	v_rcp_f32_e32 v57, v57
	s_waitcnt lgkmcnt(0)
	v_lshlrev_b32_e32 v61, 16, v39
	v_lshlrev_b32_e32 v60, 16, v59
	v_pk_fma_f32 v[6:7], v[38:39], v[60:61], v[6:7] op_sel_hi:[0,1,1]
	v_pk_mul_f32 v[54:55], v[56:57], v[54:55]
	v_and_b32_e32 v57, 0xffff0000, v183
	v_mul_f32_e32 v39, 0xbfb8aa3b, v57
	v_lshlrev_b32_e32 v56, 16, v183
	v_exp_f32_e32 v39, v39
	v_mul_f32_e32 v58, 0xbfb8aa3b, v56
	v_exp_f32_e32 v58, v58
	v_pk_mul_f32 v[28:29], v[24:25], v[24:25]
	v_add_f32_e32 v39, 1.0, v39
	v_rcp_f32_e32 v59, v39
	v_bitop3_b32 v39, v108, 48, 56 bitop3:0x6c
	v_add_f32_e32 v58, 1.0, v58
	v_lshl_add_u32 v39, v39, 1, v244
	v_rcp_f32_e32 v58, v58
	ds_read_u16 v61, v39
	ds_read_u16 v62, v39 offset:144
	v_add_f32_e32 v36, v36, v49
	v_pk_mul_f32 v[26:27], v[26:27], v[30:31]
	v_pk_mul_f32 v[56:57], v[58:59], v[56:57]
	v_lshlrev_b32_e32 v58, 16, v180
	v_and_b32_e32 v59, 0xffff0000, v180
	v_mul_f32_e32 v60, 0xbfb8aa3b, v58
	s_waitcnt lgkmcnt(0)
; __device__ __forceinline__ float bf2f(unsigned v) { return __uint_as_float(v << 16); }
; __device__ __forceinline__ float silu_f(float v) { return v * __builtin_amdgcn_rcpf(1.f + __builtin_amdgcn_exp2f(-1.4426950409f * v)); }
; __device__ __forceinline__ void ssd_passC_unit(const Args& a, LAS unsigned char* lds, int unit, int tid, int w4, int lane, LAS unsigned* bcnt, unsigned& btarget) {
;     ...
;             for (int j = 0; j < 4; ++j) { const float xv = bf2f(XT[(p0 + j) * XT_LD + ((((l >> 3) ^ ((pt * 4 + i) & 7)) << 3) | (l & 7))]); const float y = (ya[pt][4 * i + j] + Dh * xv) * silu_f(zv[j]); ya[pt][4 * i + j] = y; ssq += y * y; }
;         }
;     ssq += __shfl_xor(ssq, 32);
;     if (hf == 0) red[h4 * 64 + l] = ssq;
;     sub_barrier(bcnt, btarget, lane);
;     const float* nw0 = a.in[I_SNW] + g * 256 + h4 * 64;
;     const float tot = red[l] + red[64 + l] + red[128 + l] + red[192 + l];
;     const float rs = 1.f / sqrtf(tot * (1.f / 256.f) + EPS);
;     if (realtok) {
;         bf16_t* orow = (bf16_t*)(a.ws + WS_MIXIN) + (size_t)row * DM + g * 256 + h4 * 64;
; #pragma unroll
;         for (int pt = 0; pt < 2; ++pt)
; #pragma unroll
;             for (int i = 0; i < 4; ++i) { const int p0 = pt * 32 + 8 * i + 4 * hf; const f32x4 nq = *(const f32x4*)(nw0 + p0);
	v_lshlrev_b32_e32 v63, 16, v62
	v_lshlrev_b32_e32 v62, 16, v61
	v_mul_f32_e32 v61, 0xbfb8aa3b, v59
	v_exp_f32_e32 v60, v60
	v_exp_f32_e32 v61, v61
	v_pk_fma_f32 v[8:9], v[38:39], v[62:63], v[8:9] op_sel_hi:[0,1,1]
	ds_read_u16 v63, v39 offset:288
	ds_read_u16 v39, v39 offset:432
	v_add_f32_e32 v60, 1.0, v60
	v_add_f32_e32 v61, 1.0, v61
	v_rcp_f32_e32 v60, v60
	v_rcp_f32_e32 v61, v61
	s_waitcnt lgkmcnt(0)
	v_lshlrev_b32_e32 v65, 16, v39
	v_lshlrev_b32_e32 v64, 16, v63
	v_pk_fma_f32 v[10:11], v[38:39], v[64:65], v[10:11] op_sel_hi:[0,1,1]
	v_pk_mul_f32 v[58:59], v[60:61], v[58:59]
	v_and_b32_e32 v61, 0xffff0000, v181
	v_mul_f32_e32 v39, 0xbfb8aa3b, v61
	v_lshlrev_b32_e32 v60, 16, v181
	v_exp_f32_e32 v39, v39
	v_mul_f32_e32 v62, 0xbfb8aa3b, v60
	v_exp_f32_e32 v62, v62
	v_add_f32_e32 v28, v36, v28
	v_add_f32_e32 v39, 1.0, v39
	v_rcp_f32_e32 v63, v39
	v_bitop3_b32 v39, v108, 56, v108 bitop3:0xc
	v_add_f32_e32 v62, 1.0, v62
	v_lshl_add_u32 v39, v39, 1, v245
	v_rcp_f32_e32 v62, v62
	ds_read_u16 v65, v39
	ds_read_u16 v66, v39 offset:144
	v_pk_mul_f32 v[30:31], v[26:27], v[26:27]
	v_add_f32_e32 v28, v28, v29
	v_pk_mul_f32 v[60:61], v[62:63], v[60:61]
	v_lshlrev_b32_e32 v62, 16, v178
	v_and_b32_e32 v63, 0xffff0000, v178
	v_mul_f32_e32 v64, 0xbfb8aa3b, v62
	s_waitcnt lgkmcnt(0)
	v_lshlrev_b32_e32 v67, 16, v66
	v_lshlrev_b32_e32 v66, 16, v65
	v_mul_f32_e32 v65, 0xbfb8aa3b, v63
	v_exp_f32_e32 v64, v64
	v_exp_f32_e32 v65, v65
	v_pk_fma_f32 v[12:13], v[38:39], v[66:67], v[12:13] op_sel_hi:[0,1,1]
	ds_read_u16 v67, v39 offset:288
	ds_read_u16 v39, v39 offset:432
	v_add_f32_e32 v64, 1.0, v64
	v_add_f32_e32 v65, 1.0, v65
	v_rcp_f32_e32 v64, v64
	v_rcp_f32_e32 v65, v65
	v_pk_mul_f32 v[0:1], v[50:51], v[0:1]
	v_add_f32_e32 v28, v28, v30
	v_pk_mul_f32 v[50:51], v[0:1], v[0:1]
	v_add_f32_e32 v28, v28, v31
	v_pk_mul_f32 v[2:3], v[52:53], v[2:3]
	v_pk_mul_f32 v[62:63], v[64:65], v[62:63]
	v_lshlrev_b32_e32 v64, 16, v179
	v_and_b32_e32 v65, 0xffff0000, v179
	s_waitcnt lgkmcnt(0)
	v_lshlrev_b32_e32 v69, 16, v39
	v_lshlrev_b32_e32 v68, 16, v67
	v_add_f32_e32 v28, v28, v50
	v_pk_mul_f32 v[52:53], v[2:3], v[2:3]
	v_mul_f32_e32 v66, 0xbfb8aa3b, v64
	v_pk_fma_f32 v[14:15], v[38:39], v[68:69], v[14:15] op_sel_hi:[0,1,1]
	v_mul_f32_e32 v38, 0xbfb8aa3b, v65
	v_add_f32_e32 v28, v28, v51
	v_pk_mul_f32 v[4:5], v[54:55], v[4:5]
	v_exp_f32_e32 v66, v66
	v_exp_f32_e32 v38, v38
	v_add_f32_e32 v28, v28, v52
	v_pk_mul_f32 v[54:55], v[4:5], v[4:5]
	v_add_f32_e32 v28, v28, v53
	v_pk_mul_f32 v[6:7], v[56:57], v[6:7]
	v_add_f32_e32 v28, v28, v54
	v_pk_mul_f32 v[56:57], v[6:7], v[6:7]
	v_add_f32_e32 v28, v28, v55
	v_pk_mul_f32 v[8:9], v[58:59], v[8:9]
	v_add_f32_e32 v66, 1.0, v66
	v_add_f32_e32 v38, 1.0, v38
	v_add_f32_e32 v28, v28, v56
	v_pk_mul_f32 v[58:59], v[8:9], v[8:9]
	v_rcp_f32_e32 v66, v66
	v_rcp_f32_e32 v67, v38
	v_add_f32_e32 v28, v28, v57
	v_pk_mul_f32 v[10:11], v[60:61], v[10:11]
	v_add_f32_e32 v28, v28, v58
	v_pk_mul_f32 v[60:61], v[10:11], v[10:11]
	v_add_f32_e32 v28, v28, v59
	v_pk_mul_f32 v[12:13], v[62:63], v[12:13]
	v_add_f32_e32 v28, v28, v60
	v_pk_mul_f32 v[62:63], v[12:13], v[12:13]
	v_pk_mul_f32 v[38:39], v[66:67], v[64:65]
	v_add_f32_e32 v28, v28, v61
	v_pk_mul_f32 v[14:15], v[38:39], v[14:15]
	v_add_f32_e32 v28, v28, v62
	v_pk_mul_f32 v[38:39], v[14:15], v[14:15]
	v_add_f32_e32 v28, v28, v63
	v_add_f32_e32 v28, v28, v38
	v_add_f32_e32 v28, v28, v39
	global_load_dwordx4 v[40:43], v[100:101], off
	global_load_dwordx4 v[44:47], v[102:103], off
	global_load_dwordx4 v[48:51], v[104:105], off
	global_load_dwordx4 v[52:55], v[164:165], off
	global_load_dwordx4 v[56:59], v[166:167], off
	global_load_dwordx4 v[60:63], v[168:169], off
	global_load_dwordx4 v[64:67], v[170:171], off
	global_load_dwordx4 v[180:183], v[172:173], off
	ds_bpermute_b32 v29, v251, v28
	s_and_saveexec_b64 s[54:55], s[2:3]
	s_cbranch_execz .LBB0_844
	s_waitcnt lgkmcnt(0)
	v_add_f32_e32 v28, v28, v29
	v_lshl_add_u32 v29, v108, 2, s95
	ds_write_b32 v29, v28

; __device__ __forceinline__ unsigned pk2(float lo, float hi) { f32x2 v; v.x = lo; v.y = hi; return __builtin_bit_cast(unsigned, __builtin_convertvector(v, hwbf2)); }
; __device__ __forceinline__ void ssd_passC_unit(const Args& a, LAS unsigned char* lds, int unit, int tid, int w4, int lane, LAS unsigned* bcnt, unsigned& btarget) {
;     ...
;     const float tot = red[l] + red[64 + l] + red[128 + l] + red[192 + l];
;     const float rs = 1.f / sqrtf(tot * (1.f / 256.f) + EPS);
;     if (realtok) {
;         bf16_t* orow = (bf16_t*)(a.ws + WS_MIXIN) + (size_t)row * DM + g * 256 + h4 * 64;
; #pragma unroll
;         for (int pt = 0; pt < 2; ++pt)
; #pragma unroll
;             for (int i = 0; i < 4; ++i) { const int p0 = pt * 32 + 8 * i + 4 * hf; const f32x4 nq = *(const f32x4*)(nw0 + p0);
;                 u32x2 w; w.x = pk2(ya[pt][4 * i] * rs * nq[0], ya[pt][4 * i + 1] * rs * nq[1]); w.y = pk2(ya[pt][4 * i + 2] * rs * nq[2], ya[pt][4 * i + 3] * rs * nq[3]);
;                 *(u32x2*)(orow + p0) = w; }
.LBB0_851:
	s_waitcnt vmcnt(0)
	v_cmp_le_u32_e32 vcc, s92, v108
	s_and_saveexec_b64 s[58:59], vcc
	s_cbranch_execz .LBB0_839
	v_lshl_add_u32 v30, v108, 2, s94
	ds_read2st64_b32 v[28:29], v30 offset1:1
	s_mov_b32 s0, 0xf800000
	v_lshlrev_b32_e32 v108, 1, v106
	s_waitcnt lgkmcnt(0)
	v_add_f32_e32 v31, v28, v29
	ds_read2st64_b32 v[28:29], v30 offset0:2 offset1:3
	s_waitcnt lgkmcnt(0)
	v_add_f32_e32 v28, v31, v28
	v_add_f32_e32 v28, v28, v29
	v_fmamk_f32 v28, v28, 0x3b800000, v249
	v_cmp_gt_f32_e32 vcc, s0, v28
	v_mul_f32_e32 v29, 0x4f800000, v28
	s_nop 0
	v_cndmask_b32_e32 v28, v28, v29, vcc
	v_sqrt_f32_e32 v29, v28
	s_nop 0
	v_add_u32_e32 v30, -1, v29
	v_fma_f32 v31, -v30, v29, v28
	v_cmp_ge_f32_e64 s[0:1], 0, v31
	v_add_u32_e32 v31, 1, v29
	s_nop 0
	v_cndmask_b32_e64 v30, v29, v30, s[0:1]
	v_fma_f32 v29, -v31, v29, v28
	v_cmp_lt_f32_e64 s[0:1], 0, v29
	s_nop 1
	v_cndmask_b32_e64 v29, v30, v31, s[0:1]
	v_mul_f32_e32 v30, 0x37800000, v29
	v_cndmask_b32_e32 v29, v29, v30, vcc
	v_cmp_class_f32_e32 vcc, v28, v250
	s_nop 1
	v_cndmask_b32_e32 v28, v29, v28, vcc
	v_div_scale_f32 v29, s[0:1], v28, v28, 1.0
	v_rcp_f32_e32 v30, v29
	s_nop 0
	v_fma_f32 v31, -v29, v30, 1.0
	v_fmac_f32_e32 v30, v31, v30
	v_div_scale_f32 v31, vcc, 1.0, v28, 1.0
	v_mul_f32_e32 v36, v31, v30
	v_fma_f32 v37, -v29, v36, v31
	v_fmac_f32_e32 v36, v37, v30
	v_fma_f32 v29, -v29, v36, v31
	v_div_fmas_f32 v29, v29, v30, v36
	v_div_fixup_f32 v30, v29, v28, 1.0
	v_lshlrev_b64 v[28:29], 11, v[174:175]
	v_pk_mul_f32 v[32:33], v[32:33], v[30:31] op_sel_hi:[1,0]
	v_pk_mul_f32 v[34:35], v[34:35], v[30:31] op_sel_hi:[1,0]
	v_lshl_add_u64 v[28:29], s[52:53], 0, v[28:29]
	v_pk_mul_f32 v[16:17], v[16:17], v[30:31] op_sel_hi:[1,0]
	v_pk_mul_f32 v[18:19], v[18:19], v[30:31] op_sel_hi:[1,0]
	v_pk_mul_f32 v[20:21], v[20:21], v[30:31] op_sel_hi:[1,0]
	v_pk_mul_f32 v[0:1], v[0:1], v[30:31] op_sel_hi:[1,0]
	v_pk_mul_f32 v[2:3], v[2:3], v[30:31] op_sel_hi:[1,0]
	v_pk_mul_f32 v[4:5], v[4:5], v[30:31] op_sel_hi:[1,0]
	v_pk_mul_f32 v[32:33], v[40:41], v[32:33]
	v_pk_mul_f32 v[34:35], v[42:43], v[34:35]
	v_cvt_pk_bf16_f32 v32, v32, v33
	v_cvt_pk_bf16_f32 v33, v34, v35
	v_lshl_add_u64 v[34:35], v[28:29], 0, v[108:109]
	global_store_dwordx2 v[34:35], v[32:33], off
	v_lshlrev_b32_e32 v108, 1, v112
	v_pk_mul_f32 v[16:17], v[44:45], v[16:17]
	v_pk_mul_f32 v[18:19], v[46:47], v[18:19]
	v_cvt_pk_bf16_f32 v16, v16, v17
	v_cvt_pk_bf16_f32 v17, v18, v19
	v_lshl_add_u64 v[18:19], v[28:29], 0, v[108:109]
	global_store_dwordx2 v[18:19], v[16:17], off
	v_lshlrev_b32_e32 v108, 1, v116
	v_pk_mul_f32 v[16:17], v[20:21], v[48:49]
	v_pk_mul_f32 v[20:21], v[22:23], v[30:31] op_sel_hi:[1,0]
	v_cvt_pk_bf16_f32 v16, v16, v17
	v_pk_mul_f32 v[18:19], v[20:21], v[50:51]
	v_pk_mul_f32 v[20:21], v[24:25], v[30:31] op_sel_hi:[1,0]
	v_cvt_pk_bf16_f32 v17, v18, v19
	v_lshl_add_u64 v[18:19], v[28:29], 0, v[108:109]
	global_store_dwordx2 v[18:19], v[16:17], off
	v_lshlrev_b32_e32 v108, 1, v120
	v_pk_mul_f32 v[16:17], v[20:21], v[52:53]
	v_pk_mul_f32 v[20:21], v[26:27], v[30:31] op_sel_hi:[1,0]
	v_cvt_pk_bf16_f32 v16, v16, v17
	v_pk_mul_f32 v[18:19], v[20:21], v[54:55]
	s_nop 0
	v_cvt_pk_bf16_f32 v17, v18, v19
	v_lshl_add_u64 v[18:19], v[28:29], 0, v[108:109]
	global_store_dwordx2 v[18:19], v[16:17], off
	v_lshlrev_b32_e32 v108, 1, v124
	v_pk_mul_f32 v[0:1], v[0:1], v[56:57]
	v_pk_mul_f32 v[2:3], v[2:3], v[58:59]
	v_cvt_pk_bf16_f32 v0, v0, v1
	v_cvt_pk_bf16_f32 v1, v2, v3
	v_lshl_add_u64 v[2:3], v[28:29], 0, v[108:109]
	global_store_dwordx2 v[2:3], v[0:1], off
	v_lshlrev_b32_e32 v108, 1, v128
	v_pk_mul_f32 v[0:1], v[4:5], v[60:61]
	v_pk_mul_f32 v[4:5], v[6:7], v[30:31] op_sel_hi:[1,0]
	v_cvt_pk_bf16_f32 v0, v0, v1
	v_pk_mul_f32 v[2:3], v[4:5], v[62:63]
	v_pk_mul_f32 v[4:5], v[8:9], v[30:31] op_sel_hi:[1,0]
	v_cvt_pk_bf16_f32 v1, v2, v3
	v_lshl_add_u64 v[2:3], v[28:29], 0, v[108:109]
	global_store_dwordx2 v[2:3], v[0:1], off
	v_lshlrev_b32_e32 v108, 1, v132
	v_pk_mul_f32 v[0:1], v[4:5], v[64:65]
	v_pk_mul_f32 v[4:5], v[10:11], v[30:31] op_sel_hi:[1,0]
	v_cvt_pk_bf16_f32 v0, v0, v1
	v_pk_mul_f32 v[2:3], v[4:5], v[66:67]
	v_pk_mul_f32 v[4:5], v[12:13], v[30:31] op_sel_hi:[1,0]
	v_cvt_pk_bf16_f32 v1, v2, v3
	v_lshl_add_u64 v[2:3], v[28:29], 0, v[108:109]
	global_store_dwordx2 v[2:3], v[0:1], off
	v_lshlrev_b32_e32 v108, 1, v136
	v_pk_mul_f32 v[0:1], v[4:5], v[180:181]
	v_pk_mul_f32 v[4:5], v[14:15], v[30:31] op_sel_hi:[1,0]
	v_cvt_pk_bf16_f32 v0, v0, v1
	v_pk_mul_f32 v[2:3], v[4:5], v[182:183]
	s_nop 0
	v_cvt_pk_bf16_f32 v1, v2, v3
	v_lshl_add_u64 v[2:3], v[28:29], 0, v[108:109]
	global_store_dwordx2 v[2:3], v[0:1], off
	s_branch .LBB0_839
